# GEMM main loops: per-phase s_setprio flips removed and one static raise for waves 0-3
# baseline (speedup 1.0000x reference)
.LBB0_97:
	s_ashr_i32 s23, s22, 31
	s_lshl_b64 s[4:5], s[22:23], 19
	v_readlane_b32 s12, v253, 58
	v_cmp_lt_i64_e32 vcc, s[38:39], v[170:171]
	v_readlane_b32 s13, v253, 59
	s_add_u32 s38, s12, s4
	s_addc_u32 s39, s13, s5
	s_and_b64 s[4:5], vcc, exec
	s_cselect_b32 s23, s39, s45
	s_cselect_b32 s51, s38, s44
	s_ashr_i32 s25, s24, 31
	s_lshl_b64 s[4:5], s[24:25], 19
	s_add_u32 s42, s7, s4
	s_addc_u32 s43, s10, s5
	s_and_b64 s[4:5], vcc, exec
	s_cselect_b32 s25, s43, s47
	s_cselect_b32 s52, s42, s46
	s_add_u32 s44, s44, 0x40080
	s_addc_u32 s45, s45, 0
	s_add_u32 s53, s46, 0x100
	v_mov_b32_e32 v2, 0
	s_addc_u32 s54, s47, 0
	s_mov_b32 s55, -2
	v_mov_b32_e32 v3, v2
	v_mov_b32_e32 v4, v2
	v_mov_b32_e32 v5, v2
	v_mov_b32_e32 v10, v2
	v_mov_b32_e32 v11, v2
	v_mov_b32_e32 v12, v2
	v_mov_b32_e32 v13, v2
	v_mov_b32_e32 v18, v2
	v_mov_b32_e32 v19, v2
	v_mov_b32_e32 v20, v2
	v_mov_b32_e32 v21, v2
	v_mov_b32_e32 v26, v2
	v_mov_b32_e32 v27, v2
	v_mov_b32_e32 v28, v2
	v_mov_b32_e32 v29, v2
	v_mov_b32_e32 v34, v2
	v_mov_b32_e32 v35, v2
	v_mov_b32_e32 v36, v2
	v_mov_b32_e32 v37, v2
	v_mov_b32_e32 v42, v2
	v_mov_b32_e32 v43, v2
	v_mov_b32_e32 v44, v2
	v_mov_b32_e32 v45, v2
	v_mov_b32_e32 v50, v2
	v_mov_b32_e32 v51, v2
	v_mov_b32_e32 v52, v2
	v_mov_b32_e32 v53, v2
	v_mov_b32_e32 v58, v2
	v_mov_b32_e32 v59, v2
	v_mov_b32_e32 v60, v2
	v_mov_b32_e32 v61, v2
	v_mov_b32_e32 v6, v2
	v_mov_b32_e32 v7, v2
	v_mov_b32_e32 v8, v2
	v_mov_b32_e32 v9, v2
	v_mov_b32_e32 v14, v2
	v_mov_b32_e32 v15, v2
	v_mov_b32_e32 v16, v2
	v_mov_b32_e32 v17, v2
	v_mov_b32_e32 v22, v2
	v_mov_b32_e32 v23, v2
	v_mov_b32_e32 v24, v2
	v_mov_b32_e32 v25, v2
	v_mov_b32_e32 v30, v2
	v_mov_b32_e32 v31, v2
	v_mov_b32_e32 v32, v2
	v_mov_b32_e32 v33, v2
	v_mov_b32_e32 v38, v2
	v_mov_b32_e32 v39, v2
	v_mov_b32_e32 v40, v2
	v_mov_b32_e32 v41, v2
	v_mov_b32_e32 v46, v2
	v_mov_b32_e32 v47, v2
	v_mov_b32_e32 v48, v2
	v_mov_b32_e32 v49, v2
	v_mov_b32_e32 v54, v2
	v_mov_b32_e32 v55, v2
	v_mov_b32_e32 v56, v2
	v_mov_b32_e32 v57, v2
	v_mov_b32_e32 v62, v2
	v_mov_b32_e32 v63, v2
	v_mov_b32_e32 v64, v2
	v_mov_b32_e32 v65, v2
	v_mov_b32_e32 v66, v2
	v_mov_b32_e32 v67, v2
	v_mov_b32_e32 v68, v2
	v_mov_b32_e32 v69, v2
	v_mov_b32_e32 v74, v2
	v_mov_b32_e32 v75, v2
	v_mov_b32_e32 v76, v2
	v_mov_b32_e32 v77, v2
	v_mov_b32_e32 v82, v2
	v_mov_b32_e32 v83, v2
	v_mov_b32_e32 v84, v2
	v_mov_b32_e32 v85, v2
	v_mov_b32_e32 v90, v2
	v_mov_b32_e32 v91, v2
	v_mov_b32_e32 v92, v2
	v_mov_b32_e32 v93, v2
	v_mov_b32_e32 v98, v2
	v_mov_b32_e32 v99, v2
	v_mov_b32_e32 v100, v2
	v_mov_b32_e32 v101, v2
	v_mov_b32_e32 v106, v2
	v_mov_b32_e32 v107, v2
	v_mov_b32_e32 v108, v2
	v_mov_b32_e32 v109, v2
	v_mov_b32_e32 v114, v2
	v_mov_b32_e32 v115, v2
	v_mov_b32_e32 v116, v2
	v_mov_b32_e32 v117, v2
	v_mov_b32_e32 v122, v2
	v_mov_b32_e32 v123, v2
	v_mov_b32_e32 v124, v2
	v_mov_b32_e32 v125, v2
	v_mov_b32_e32 v70, v2
	v_mov_b32_e32 v71, v2
	v_mov_b32_e32 v72, v2
	v_mov_b32_e32 v73, v2
	v_mov_b32_e32 v78, v2
	v_mov_b32_e32 v79, v2
	v_mov_b32_e32 v80, v2
	v_mov_b32_e32 v81, v2
	v_mov_b32_e32 v86, v2
	v_mov_b32_e32 v87, v2
	v_mov_b32_e32 v88, v2
	v_mov_b32_e32 v89, v2
	v_mov_b32_e32 v94, v2
	v_mov_b32_e32 v95, v2
	v_mov_b32_e32 v96, v2
	v_mov_b32_e32 v97, v2
	v_mov_b32_e32 v102, v2
	v_mov_b32_e32 v103, v2
	v_mov_b32_e32 v104, v2
	v_mov_b32_e32 v105, v2
	v_mov_b32_e32 v110, v2
	v_mov_b32_e32 v111, v2
	v_mov_b32_e32 v112, v2
	v_mov_b32_e32 v113, v2
	v_mov_b32_e32 v118, v2
	v_mov_b32_e32 v119, v2
	v_mov_b32_e32 v120, v2
	v_mov_b32_e32 v121, v2
	v_mov_b32_e32 v126, v2
	v_mov_b32_e32 v127, v2
	v_mov_b32_e32 v128, v2
	v_mov_b32_e32 v129, v2
	v_readfirstlane_b32 s98, v202
	s_nop 3
	s_bfe_u32 s98, s98, 0x40006
	s_cmp_ge_u32 s98, 4
	s_cbranch_scc1 .Lgp_f1
	s_setprio 1
.Lgp_f1:
.LBB0_98:
	s_add_u32 s4, s44, 0xfffc0080
	s_addc_u32 s5, s45, -1
	s_add_i32 s12, 0, 0x10000
	v_add_u32_e32 v140, s12, v143
	ds_read_b128 v[146:149], v140
	ds_read_b128 v[150:153], v140 offset:1024
	ds_read_b128 v[154:157], v140 offset:2048
	ds_read_b128 v[158:161], v140 offset:3072
	s_cmp_eq_u32 s55, 12
	s_cselect_b32 s49, s23, s5
	s_cselect_b32 s48, s51, s4
	s_cselect_b32 s47, s25, s54
	s_cselect_b32 s46, s52, s53
	v_lshl_add_u64 v[140:141], s[44:45], 0, v[136:137]
	s_add_i32 m0, s11, 0xc000
	ds_read_b128 v[162:165], v145
	ds_read_b128 v[166:169], v145 offset:1024
	ds_read_b128 v[176:179], v145 offset:2048
	ds_read_b128 v[180:183], v145 offset:3072
	ds_read_b128 v[184:187], v145 offset:4096
	ds_read_b128 v[188:191], v145 offset:5120
	ds_read_b128 v[192:195], v145 offset:6144
	ds_read_b128 v[196:199], v145 offset:7168
	global_load_lds_dwordx4 v[140:141], off
	v_lshl_add_u64 v[140:141], s[44:45], 0, v[138:139]
	s_add_i32 m0, s11, 0xe000
	s_nop 0
	global_load_lds_dwordx4 v[140:141], off
	s_waitcnt lgkmcnt(8)
	s_barrier
	s_waitcnt lgkmcnt(0)
	s_waitcnt lgkmcnt(0)
	v_mfma_f32_16x16x32_bf16 v[126:129], v[146:149], v[162:165], v[126:129]
	v_mfma_f32_16x16x32_bf16 v[118:121], v[154:157], v[162:165], v[118:121]
	v_mfma_f32_16x16x32_bf16 v[110:113], v[146:149], v[176:179], v[110:113]
	v_mfma_f32_16x16x32_bf16 v[102:105], v[154:157], v[176:179], v[102:105]
	v_mfma_f32_16x16x32_bf16 v[94:97], v[146:149], v[184:187], v[94:97]
	v_mfma_f32_16x16x32_bf16 v[86:89], v[154:157], v[184:187], v[86:89]
	v_mfma_f32_16x16x32_bf16 v[78:81], v[146:149], v[192:195], v[78:81]
	v_mfma_f32_16x16x32_bf16 v[70:73], v[154:157], v[192:195], v[70:73]
	v_mfma_f32_16x16x32_bf16 v[126:129], v[150:153], v[166:169], v[126:129]
	v_mfma_f32_16x16x32_bf16 v[118:121], v[158:161], v[166:169], v[118:121]
	v_mfma_f32_16x16x32_bf16 v[110:113], v[150:153], v[180:183], v[110:113]
	v_mfma_f32_16x16x32_bf16 v[102:105], v[158:161], v[180:183], v[102:105]
	v_mfma_f32_16x16x32_bf16 v[94:97], v[150:153], v[188:191], v[94:97]
	v_mfma_f32_16x16x32_bf16 v[86:89], v[158:161], v[188:191], v[86:89]
	v_mfma_f32_16x16x32_bf16 v[78:81], v[150:153], v[196:199], v[78:81]
	v_mfma_f32_16x16x32_bf16 v[70:73], v[158:161], v[196:199], v[70:73]
	s_barrier
	s_add_i32 s13, 0, 0x14000
	v_add_u32_e32 v140, s13, v143
	s_add_i32 s4, s12, s6
	ds_read_b128 v[228:231], v140
	ds_read_b128 v[232:235], v140 offset:1024
	ds_read_b128 v[236:239], v140 offset:2048
	ds_read_b128 v[240:243], v140 offset:3072
	v_lshl_add_u64 v[140:141], s[46:47], 0, v[0:1]
	s_mov_b32 m0, s4
	v_lshl_add_u64 v[200:201], s[46:47], 0, v[130:131]
	global_load_lds_dwordx4 v[140:141], off
	s_add_i32 m0, s4, 0x2000
	s_nop 0
	global_load_lds_dwordx4 v[200:201], off
	s_barrier
	s_waitcnt lgkmcnt(0)
	s_waitcnt lgkmcnt(0)
	v_mfma_f32_16x16x32_bf16 v[122:125], v[228:231], v[162:165], v[122:125]
	v_mfma_f32_16x16x32_bf16 v[114:117], v[236:239], v[162:165], v[114:117]
	v_mfma_f32_16x16x32_bf16 v[106:109], v[228:231], v[176:179], v[106:109]
	v_mfma_f32_16x16x32_bf16 v[98:101], v[236:239], v[176:179], v[98:101]
	v_mfma_f32_16x16x32_bf16 v[90:93], v[228:231], v[184:187], v[90:93]
	v_mfma_f32_16x16x32_bf16 v[82:85], v[236:239], v[184:187], v[82:85]
	v_mfma_f32_16x16x32_bf16 v[74:77], v[228:231], v[192:195], v[74:77]
	v_mfma_f32_16x16x32_bf16 v[66:69], v[236:239], v[192:195], v[66:69]
	v_mfma_f32_16x16x32_bf16 v[122:125], v[232:235], v[166:169], v[122:125]
	v_mfma_f32_16x16x32_bf16 v[114:117], v[240:243], v[166:169], v[114:117]
	v_mfma_f32_16x16x32_bf16 v[106:109], v[232:235], v[180:183], v[106:109]
	v_mfma_f32_16x16x32_bf16 v[98:101], v[240:243], v[180:183], v[98:101]
	v_mfma_f32_16x16x32_bf16 v[90:93], v[232:235], v[188:191], v[90:93]
	v_mfma_f32_16x16x32_bf16 v[82:85], v[240:243], v[188:191], v[82:85]
	v_mfma_f32_16x16x32_bf16 v[74:77], v[232:235], v[196:199], v[74:77]
	v_mfma_f32_16x16x32_bf16 v[66:69], v[240:243], v[196:199], v[66:69]
	s_mov_b32 m0, s11
	v_lshl_add_u64 v[244:245], s[48:49], 0, v[134:135]
	s_barrier
	ds_read_b128 v[162:165], v145 offset:16384
	ds_read_b128 v[166:169], v145 offset:17408
	ds_read_b128 v[176:179], v145 offset:18432
	ds_read_b128 v[180:183], v145 offset:19456
	ds_read_b128 v[184:187], v145 offset:20480
	ds_read_b128 v[188:191], v145 offset:21504
	ds_read_b128 v[192:195], v145 offset:22528
	ds_read_b128 v[196:199], v145 offset:23552
	global_load_lds_dwordx4 v[244:245], off
	v_lshl_add_u64 v[246:247], s[48:49], 0, v[132:133]
	s_mov_b32 m0, s14
	s_nop 0
	global_load_lds_dwordx4 v[246:247], off
	s_barrier
	s_waitcnt lgkmcnt(0)
	s_waitcnt lgkmcnt(0)
	v_mfma_f32_16x16x32_bf16 v[62:65], v[146:149], v[162:165], v[62:65]
	v_mfma_f32_16x16x32_bf16 v[54:57], v[154:157], v[162:165], v[54:57]
	v_mfma_f32_16x16x32_bf16 v[46:49], v[146:149], v[176:179], v[46:49]
	v_mfma_f32_16x16x32_bf16 v[38:41], v[154:157], v[176:179], v[38:41]
	v_mfma_f32_16x16x32_bf16 v[30:33], v[146:149], v[184:187], v[30:33]
	v_mfma_f32_16x16x32_bf16 v[22:25], v[154:157], v[184:187], v[22:25]
	v_mfma_f32_16x16x32_bf16 v[14:17], v[146:149], v[192:195], v[14:17]
	v_mfma_f32_16x16x32_bf16 v[6:9], v[154:157], v[192:195], v[6:9]
	v_mfma_f32_16x16x32_bf16 v[62:65], v[150:153], v[166:169], v[62:65]
	v_mfma_f32_16x16x32_bf16 v[54:57], v[158:161], v[166:169], v[54:57]
	v_mfma_f32_16x16x32_bf16 v[46:49], v[150:153], v[180:183], v[46:49]
	v_mfma_f32_16x16x32_bf16 v[38:41], v[158:161], v[180:183], v[38:41]
	v_mfma_f32_16x16x32_bf16 v[30:33], v[150:153], v[188:191], v[30:33]
	v_mfma_f32_16x16x32_bf16 v[22:25], v[158:161], v[188:191], v[22:25]
	v_mfma_f32_16x16x32_bf16 v[14:17], v[150:153], v[196:199], v[14:17]
	v_mfma_f32_16x16x32_bf16 v[6:9], v[158:161], v[196:199], v[6:9]
	s_barrier
	s_add_u32 s4, s46, 0x40000
	s_addc_u32 s5, s47, 0
	s_add_i32 s12, s13, s6
	v_lshl_add_u64 v[146:147], s[4:5], 0, v[0:1]
	s_mov_b32 m0, s12
	s_nop 0
	global_load_lds_dwordx4 v[146:147], off
	v_lshl_add_u64 v[146:147], s[4:5], 0, v[130:131]
	s_add_i32 m0, s12, 0x2000
	s_nop 0
	global_load_lds_dwordx4 v[146:147], off
	s_waitcnt vmcnt(6)
	s_barrier
	v_mfma_f32_16x16x32_bf16 v[58:61], v[228:231], v[162:165], v[58:61]
	v_mfma_f32_16x16x32_bf16 v[50:53], v[236:239], v[162:165], v[50:53]
	v_mfma_f32_16x16x32_bf16 v[42:45], v[228:231], v[176:179], v[42:45]
	v_mfma_f32_16x16x32_bf16 v[34:37], v[236:239], v[176:179], v[34:37]
	v_mfma_f32_16x16x32_bf16 v[26:29], v[228:231], v[184:187], v[26:29]
	v_mfma_f32_16x16x32_bf16 v[18:21], v[236:239], v[184:187], v[18:21]
	v_mfma_f32_16x16x32_bf16 v[10:13], v[228:231], v[192:195], v[10:13]
	v_mfma_f32_16x16x32_bf16 v[2:5], v[236:239], v[192:195], v[2:5]
	v_mfma_f32_16x16x32_bf16 v[58:61], v[232:235], v[166:169], v[58:61]
	v_mfma_f32_16x16x32_bf16 v[50:53], v[240:243], v[166:169], v[50:53]
	v_mfma_f32_16x16x32_bf16 v[42:45], v[232:235], v[180:183], v[42:45]
	v_mfma_f32_16x16x32_bf16 v[34:37], v[240:243], v[180:183], v[34:37]
	v_mfma_f32_16x16x32_bf16 v[26:29], v[232:235], v[188:191], v[26:29]
	v_mfma_f32_16x16x32_bf16 v[18:21], v[240:243], v[188:191], v[18:21]
	v_mfma_f32_16x16x32_bf16 v[10:13], v[232:235], v[196:199], v[10:13]
	v_mfma_f32_16x16x32_bf16 v[2:5], v[240:243], v[196:199], v[2:5]
	s_add_i32 s12, 0, 0x18000
	v_add_u32_e32 v158, s12, v143
	s_barrier
	ds_read_b128 v[146:149], v158
	ds_read_b128 v[150:153], v158 offset:1024
	ds_read_b128 v[154:157], v158 offset:2048
	ds_read_b128 v[158:161], v158 offset:3072
	s_add_u32 s4, s48, 0x40000
	s_addc_u32 s5, s49, 0
	s_mov_b32 m0, s15
	v_lshl_add_u64 v[228:229], s[4:5], 0, v[134:135]
	ds_read_b128 v[162:165], v145 offset:32768
	ds_read_b128 v[166:169], v145 offset:33792
	ds_read_b128 v[176:179], v145 offset:34816
	ds_read_b128 v[180:183], v145 offset:35840
	ds_read_b128 v[184:187], v145 offset:36864
	ds_read_b128 v[188:191], v145 offset:37888
	ds_read_b128 v[192:195], v145 offset:38912
	ds_read_b128 v[196:199], v145 offset:39936
	global_load_lds_dwordx4 v[228:229], off
	v_lshl_add_u64 v[228:229], s[4:5], 0, v[132:133]
	s_mov_b32 m0, s18
	s_nop 0
	global_load_lds_dwordx4 v[228:229], off
	s_waitcnt lgkmcnt(8)
	s_barrier
	s_waitcnt lgkmcnt(0)
	s_waitcnt lgkmcnt(0)
	v_mfma_f32_16x16x32_bf16 v[126:129], v[146:149], v[162:165], v[126:129]
	v_mfma_f32_16x16x32_bf16 v[118:121], v[154:157], v[162:165], v[118:121]
	v_mfma_f32_16x16x32_bf16 v[110:113], v[146:149], v[176:179], v[110:113]
	v_mfma_f32_16x16x32_bf16 v[102:105], v[154:157], v[176:179], v[102:105]
	v_mfma_f32_16x16x32_bf16 v[94:97], v[146:149], v[184:187], v[94:97]
	v_mfma_f32_16x16x32_bf16 v[86:89], v[154:157], v[184:187], v[86:89]
	v_mfma_f32_16x16x32_bf16 v[78:81], v[146:149], v[192:195], v[78:81]
	v_mfma_f32_16x16x32_bf16 v[70:73], v[154:157], v[192:195], v[70:73]
	v_mfma_f32_16x16x32_bf16 v[126:129], v[150:153], v[166:169], v[126:129]
	v_mfma_f32_16x16x32_bf16 v[118:121], v[158:161], v[166:169], v[118:121]
	v_mfma_f32_16x16x32_bf16 v[110:113], v[150:153], v[180:183], v[110:113]
	v_mfma_f32_16x16x32_bf16 v[102:105], v[158:161], v[180:183], v[102:105]
	v_mfma_f32_16x16x32_bf16 v[94:97], v[150:153], v[188:191], v[94:97]
	v_mfma_f32_16x16x32_bf16 v[86:89], v[158:161], v[188:191], v[86:89]
	v_mfma_f32_16x16x32_bf16 v[78:81], v[150:153], v[196:199], v[78:81]
	v_mfma_f32_16x16x32_bf16 v[70:73], v[158:161], v[196:199], v[70:73]
	s_barrier
	s_add_i32 s13, 0, 0x1c000
	s_add_i32 s4, s12, s6
	v_add_u32_e32 v175, s13, v143
	v_lshl_add_u64 v[140:141], v[140:141], 0, s[34:35]
	s_mov_b32 m0, s4
	ds_read_b128 v[228:231], v175
	ds_read_b128 v[232:235], v175 offset:1024
	ds_read_b128 v[236:239], v175 offset:2048
	ds_read_b128 v[240:243], v175 offset:3072
	global_load_lds_dwordx4 v[140:141], off
	v_lshl_add_u64 v[140:141], v[200:201], 0, s[34:35]
	s_add_i32 m0, s4, 0x2000
	s_nop 0
	global_load_lds_dwordx4 v[140:141], off
	s_barrier
	s_waitcnt lgkmcnt(0)
	s_waitcnt lgkmcnt(0)
	v_mfma_f32_16x16x32_bf16 v[122:125], v[228:231], v[162:165], v[122:125]
	v_mfma_f32_16x16x32_bf16 v[114:117], v[236:239], v[162:165], v[114:117]
	v_mfma_f32_16x16x32_bf16 v[106:109], v[228:231], v[176:179], v[106:109]
	v_mfma_f32_16x16x32_bf16 v[98:101], v[236:239], v[176:179], v[98:101]
	v_mfma_f32_16x16x32_bf16 v[90:93], v[228:231], v[184:187], v[90:93]
	v_mfma_f32_16x16x32_bf16 v[82:85], v[236:239], v[184:187], v[82:85]
	v_mfma_f32_16x16x32_bf16 v[74:77], v[228:231], v[192:195], v[74:77]
	v_mfma_f32_16x16x32_bf16 v[66:69], v[236:239], v[192:195], v[66:69]
	v_mfma_f32_16x16x32_bf16 v[122:125], v[232:235], v[166:169], v[122:125]
	v_mfma_f32_16x16x32_bf16 v[114:117], v[240:243], v[166:169], v[114:117]
	v_mfma_f32_16x16x32_bf16 v[106:109], v[232:235], v[180:183], v[106:109]
	v_mfma_f32_16x16x32_bf16 v[98:101], v[240:243], v[180:183], v[98:101]
	v_mfma_f32_16x16x32_bf16 v[90:93], v[232:235], v[188:191], v[90:93]
	v_mfma_f32_16x16x32_bf16 v[82:85], v[240:243], v[188:191], v[82:85]
	v_mfma_f32_16x16x32_bf16 v[74:77], v[232:235], v[196:199], v[74:77]
	v_mfma_f32_16x16x32_bf16 v[66:69], v[240:243], v[196:199], v[66:69]
	s_mov_b32 m0, s20
	v_lshl_add_u64 v[140:141], v[244:245], 0, s[34:35]
	s_barrier
	ds_read_b128 v[162:165], v145 offset:49152
	ds_read_b128 v[166:169], v145 offset:50176
	ds_read_b128 v[176:179], v145 offset:51200
	ds_read_b128 v[180:183], v145 offset:52224
	ds_read_b128 v[184:187], v145 offset:53248
	ds_read_b128 v[188:191], v145 offset:54272
	ds_read_b128 v[192:195], v145 offset:55296
	ds_read_b128 v[196:199], v145 offset:56320
	global_load_lds_dwordx4 v[140:141], off
	v_lshl_add_u64 v[140:141], v[246:247], 0, s[34:35]
	s_mov_b32 m0, s21
	s_nop 0
	global_load_lds_dwordx4 v[140:141], off
	s_barrier
	s_waitcnt lgkmcnt(0)
	s_waitcnt lgkmcnt(0)
	v_mfma_f32_16x16x32_bf16 v[62:65], v[146:149], v[162:165], v[62:65]
	v_mfma_f32_16x16x32_bf16 v[54:57], v[154:157], v[162:165], v[54:57]
	v_mfma_f32_16x16x32_bf16 v[46:49], v[146:149], v[176:179], v[46:49]
	v_mfma_f32_16x16x32_bf16 v[38:41], v[154:157], v[176:179], v[38:41]
	v_mfma_f32_16x16x32_bf16 v[30:33], v[146:149], v[184:187], v[30:33]
	v_mfma_f32_16x16x32_bf16 v[22:25], v[154:157], v[184:187], v[22:25]
	v_mfma_f32_16x16x32_bf16 v[14:17], v[146:149], v[192:195], v[14:17]
	v_mfma_f32_16x16x32_bf16 v[6:9], v[154:157], v[192:195], v[6:9]
	v_mfma_f32_16x16x32_bf16 v[62:65], v[150:153], v[166:169], v[62:65]
	v_mfma_f32_16x16x32_bf16 v[54:57], v[158:161], v[166:169], v[54:57]
	v_mfma_f32_16x16x32_bf16 v[46:49], v[150:153], v[180:183], v[46:49]
	v_mfma_f32_16x16x32_bf16 v[38:41], v[158:161], v[180:183], v[38:41]
	v_mfma_f32_16x16x32_bf16 v[30:33], v[150:153], v[188:191], v[30:33]
	v_mfma_f32_16x16x32_bf16 v[22:25], v[158:161], v[188:191], v[22:25]
	v_mfma_f32_16x16x32_bf16 v[14:17], v[150:153], v[196:199], v[14:17]
	v_mfma_f32_16x16x32_bf16 v[6:9], v[158:161], v[196:199], v[6:9]
	s_barrier
	s_add_u32 s4, s46, 0x40080
	s_addc_u32 s5, s47, 0
	s_add_i32 s12, s13, s6
	v_lshl_add_u64 v[140:141], s[4:5], 0, v[0:1]
	s_mov_b32 m0, s12
	s_nop 0
	global_load_lds_dwordx4 v[140:141], off
	v_lshl_add_u64 v[140:141], s[4:5], 0, v[130:131]
	s_add_i32 m0, s12, 0x2000
	s_nop 0
	global_load_lds_dwordx4 v[140:141], off
	s_waitcnt vmcnt(6)
	s_barrier
	v_mfma_f32_16x16x32_bf16 v[58:61], v[228:231], v[162:165], v[58:61]
	v_mfma_f32_16x16x32_bf16 v[50:53], v[236:239], v[162:165], v[50:53]
	v_mfma_f32_16x16x32_bf16 v[42:45], v[228:231], v[176:179], v[42:45]
	v_mfma_f32_16x16x32_bf16 v[34:37], v[236:239], v[176:179], v[34:37]
	v_mfma_f32_16x16x32_bf16 v[26:29], v[228:231], v[184:187], v[26:29]
	v_mfma_f32_16x16x32_bf16 v[18:21], v[236:239], v[184:187], v[18:21]
	v_mfma_f32_16x16x32_bf16 v[10:13], v[228:231], v[192:195], v[10:13]
	v_mfma_f32_16x16x32_bf16 v[2:5], v[236:239], v[192:195], v[2:5]
	v_mfma_f32_16x16x32_bf16 v[58:61], v[232:235], v[166:169], v[58:61]
	v_mfma_f32_16x16x32_bf16 v[50:53], v[240:243], v[166:169], v[50:53]
	v_mfma_f32_16x16x32_bf16 v[42:45], v[232:235], v[180:183], v[42:45]
	v_mfma_f32_16x16x32_bf16 v[34:37], v[240:243], v[180:183], v[34:37]
	v_mfma_f32_16x16x32_bf16 v[26:29], v[232:235], v[188:191], v[26:29]
	v_mfma_f32_16x16x32_bf16 v[18:21], v[240:243], v[188:191], v[18:21]
	v_mfma_f32_16x16x32_bf16 v[10:13], v[232:235], v[196:199], v[10:13]
	v_mfma_f32_16x16x32_bf16 v[2:5], v[240:243], v[196:199], v[2:5]
	s_add_i32 s55, s55, 2
	s_add_u32 s44, s44, 0x100
	s_addc_u32 s45, s45, 0
	s_add_u32 s53, s53, 0x100
	s_addc_u32 s54, s54, 0
	s_cmp_gt_u32 s55, 13
	s_barrier
	s_cbranch_scc0 .LBB0_98
	v_mul_f32_e32 v147, 0xbfb8aa3b, v126
	v_exp_f32_e32 v147, v147
	v_readlane_b32 s4, v254, 0
	v_lshl_or_b32 v148, s50, 7, v144
	v_readlane_b32 s5, v254, 1
	v_add_f32_e32 v147, 1.0, v147
	v_rcp_f32_e32 v152, v147
	v_mul_f32_e32 v147, 0xbfb8aa3b, v127
	v_exp_f32_e32 v147, v147
	v_lshl_add_u32 v146, s33, 8, v142
	v_ashrrev_i32_e32 v149, 31, v148
	v_mov_b64_e32 v[140:141], s[4:5]
	v_add_f32_e32 v147, 1.0, v147
	v_rcp_f32_e32 v153, v147
	s_movk_i32 s12, 0x1600
	v_mad_i64_i32 v[150:151], s[4:5], v146, s12, v[140:141]
	v_pk_mul_f32 v[126:127], v[126:127], v[152:153]
	s_and_b64 vcc, exec, s[40:41]
	v_pk_mul_f32 v[122:123], v[126:127], v[122:123]
	v_mul_f32_e32 v126, 0xbfb8aa3b, v128
	v_mul_f32_e32 v127, 0xbfb8aa3b, v129
	v_exp_f32_e32 v126, v126
	v_exp_f32_e32 v127, v127
	s_mov_b32 s50, s24
	s_mov_b32 s33, s22
	v_add_f32_e32 v126, 1.0, v126
	v_add_f32_e32 v127, 1.0, v127
	v_rcp_f32_e32 v126, v126
	v_rcp_f32_e32 v127, v127
	s_mov_b64 s[46:47], s[42:43]
	s_mov_b64 s[44:45], s[38:39]
	v_pk_mul_f32 v[126:127], v[128:129], v[126:127]
	s_nop 0
	v_pk_mul_f32 v[124:125], v[126:127], v[124:125]
	v_mul_f32_e32 v126, 0xbfb8aa3b, v118
	v_mul_f32_e32 v127, 0xbfb8aa3b, v119
	v_exp_f32_e32 v126, v126
	v_exp_f32_e32 v127, v127
	v_add_f32_e32 v126, 1.0, v126
	v_add_f32_e32 v127, 1.0, v127
	v_rcp_f32_e32 v126, v126
	v_rcp_f32_e32 v127, v127
	s_nop 0
	v_pk_mul_f32 v[118:119], v[118:119], v[126:127]
	s_nop 0
	v_pk_mul_f32 v[118:119], v[118:119], v[114:115]
	v_mul_f32_e32 v114, 0xbfb8aa3b, v120
	v_mul_f32_e32 v115, 0xbfb8aa3b, v121
	v_exp_f32_e32 v114, v114
	v_exp_f32_e32 v115, v115
	v_cvt_pk_bf16_f32 v118, v118, v119
	v_add_f32_e32 v114, 1.0, v114
	v_add_f32_e32 v115, 1.0, v115
	v_rcp_f32_e32 v114, v114
	v_rcp_f32_e32 v115, v115
	s_nop 0
	v_pk_mul_f32 v[114:115], v[120:121], v[114:115]
	s_nop 0
	v_pk_mul_f32 v[120:121], v[114:115], v[116:117]
	v_lshlrev_b64 v[114:115], 1, v[148:149]
	v_lshl_add_u64 v[126:127], v[150:151], 0, v[114:115]
	v_cvt_pk_bf16_f32 v116, v122, v123
	v_cvt_pk_bf16_f32 v117, v124, v125
	v_cvt_pk_bf16_f32 v119, v120, v121
	global_store_dwordx4 v[126:127], v[116:119], off sc1
	s_nop 1
	v_mul_f32_e32 v118, 0xbfb8aa3b, v110
	v_mul_f32_e32 v119, 0xbfb8aa3b, v111
	v_exp_f32_e32 v118, v118
	v_exp_f32_e32 v119, v119
	v_or_b32_e32 v116, 16, v146
	v_mad_i64_i32 v[116:117], s[4:5], v116, s12, v[140:141]
	v_add_f32_e32 v118, 1.0, v118
	v_add_f32_e32 v119, 1.0, v119
	v_rcp_f32_e32 v118, v118
	v_rcp_f32_e32 v119, v119
	s_nop 0
	v_pk_mul_f32 v[110:111], v[110:111], v[118:119]
	s_nop 0
	v_pk_mul_f32 v[106:107], v[110:111], v[106:107]
	v_mul_f32_e32 v110, 0xbfb8aa3b, v112
	v_mul_f32_e32 v111, 0xbfb8aa3b, v113
	v_exp_f32_e32 v110, v110
	v_exp_f32_e32 v111, v111
	v_add_f32_e32 v110, 1.0, v110
	v_add_f32_e32 v111, 1.0, v111
	v_rcp_f32_e32 v110, v110
	v_rcp_f32_e32 v111, v111
	s_nop 0
	v_pk_mul_f32 v[110:111], v[112:113], v[110:111]
	s_nop 0
	v_pk_mul_f32 v[108:109], v[110:111], v[108:109]
	v_mul_f32_e32 v110, 0xbfb8aa3b, v102
	v_mul_f32_e32 v111, 0xbfb8aa3b, v103
	v_exp_f32_e32 v110, v110
	v_exp_f32_e32 v111, v111
	v_add_f32_e32 v110, 1.0, v110
	v_add_f32_e32 v111, 1.0, v111
	v_rcp_f32_e32 v110, v110
	v_rcp_f32_e32 v111, v111
	s_nop 0
	v_pk_mul_f32 v[102:103], v[102:103], v[110:111]
	s_nop 0
	v_pk_mul_f32 v[102:103], v[102:103], v[98:99]
	v_mul_f32_e32 v98, 0xbfb8aa3b, v104
	v_mul_f32_e32 v99, 0xbfb8aa3b, v105
	v_exp_f32_e32 v98, v98
	v_exp_f32_e32 v99, v99
	v_lshl_add_u64 v[110:111], v[116:117], 0, v[114:115]
	v_add_f32_e32 v98, 1.0, v98
	v_add_f32_e32 v99, 1.0, v99
	v_rcp_f32_e32 v98, v98
	v_rcp_f32_e32 v99, v99
	s_nop 0
	v_pk_mul_f32 v[98:99], v[104:105], v[98:99]
	s_nop 0
	v_pk_mul_f32 v[104:105], v[98:99], v[100:101]
	v_cvt_pk_bf16_f32 v98, v106, v107
	v_cvt_pk_bf16_f32 v99, v108, v109
	v_cvt_pk_bf16_f32 v100, v102, v103
	v_cvt_pk_bf16_f32 v101, v104, v105
	global_store_dwordx4 v[110:111], v[98:101], off sc1
	s_nop 1
	v_mul_f32_e32 v100, 0xbfb8aa3b, v94
	v_mul_f32_e32 v101, 0xbfb8aa3b, v95
	v_exp_f32_e32 v100, v100
	v_exp_f32_e32 v101, v101
	v_or_b32_e32 v98, 32, v146
	v_mad_i64_i32 v[98:99], s[4:5], v98, s12, v[140:141]
	v_add_f32_e32 v100, 1.0, v100
	v_add_f32_e32 v101, 1.0, v101
	v_rcp_f32_e32 v100, v100
	v_rcp_f32_e32 v101, v101
	s_nop 0
	v_pk_mul_f32 v[94:95], v[94:95], v[100:101]
	s_nop 0
	v_pk_mul_f32 v[90:91], v[94:95], v[90:91]
	v_mul_f32_e32 v94, 0xbfb8aa3b, v96
	v_mul_f32_e32 v95, 0xbfb8aa3b, v97
	v_exp_f32_e32 v94, v94
	v_exp_f32_e32 v95, v95
	v_add_f32_e32 v94, 1.0, v94
	v_add_f32_e32 v95, 1.0, v95
	v_rcp_f32_e32 v94, v94
	v_rcp_f32_e32 v95, v95
	s_nop 0
	v_pk_mul_f32 v[94:95], v[96:97], v[94:95]
	s_nop 0
	v_pk_mul_f32 v[92:93], v[94:95], v[92:93]
	v_mul_f32_e32 v94, 0xbfb8aa3b, v86
	v_mul_f32_e32 v95, 0xbfb8aa3b, v87
	v_exp_f32_e32 v94, v94
	v_exp_f32_e32 v95, v95
	v_add_f32_e32 v94, 1.0, v94
	v_add_f32_e32 v95, 1.0, v95
	v_rcp_f32_e32 v94, v94
	v_rcp_f32_e32 v95, v95
	s_nop 0
	v_pk_mul_f32 v[86:87], v[86:87], v[94:95]
	s_nop 0
	v_pk_mul_f32 v[86:87], v[86:87], v[82:83]
	v_mul_f32_e32 v82, 0xbfb8aa3b, v88
	v_mul_f32_e32 v83, 0xbfb8aa3b, v89
	v_exp_f32_e32 v82, v82
	v_exp_f32_e32 v83, v83
	v_lshl_add_u64 v[94:95], v[98:99], 0, v[114:115]
	v_add_f32_e32 v82, 1.0, v82
	v_add_f32_e32 v83, 1.0, v83
	v_rcp_f32_e32 v82, v82
	v_rcp_f32_e32 v83, v83
	s_nop 0
	v_pk_mul_f32 v[82:83], v[88:89], v[82:83]
	s_nop 0
	v_pk_mul_f32 v[88:89], v[82:83], v[84:85]
	v_cvt_pk_bf16_f32 v82, v90, v91
	v_cvt_pk_bf16_f32 v83, v92, v93
	v_cvt_pk_bf16_f32 v84, v86, v87
	v_cvt_pk_bf16_f32 v85, v88, v89
	global_store_dwordx4 v[94:95], v[82:85], off sc1
	s_nop 1
	v_mul_f32_e32 v84, 0xbfb8aa3b, v78
	v_mul_f32_e32 v85, 0xbfb8aa3b, v79
	v_exp_f32_e32 v84, v84
	v_exp_f32_e32 v85, v85
	v_or_b32_e32 v82, 48, v146
	v_mad_i64_i32 v[82:83], s[4:5], v82, s12, v[140:141]
	v_add_f32_e32 v84, 1.0, v84
	v_add_f32_e32 v85, 1.0, v85
	v_rcp_f32_e32 v84, v84
	v_rcp_f32_e32 v85, v85
	s_nop 0
	v_pk_mul_f32 v[78:79], v[78:79], v[84:85]
	s_nop 0
	v_pk_mul_f32 v[74:75], v[78:79], v[74:75]
	v_mul_f32_e32 v78, 0xbfb8aa3b, v80
	v_mul_f32_e32 v79, 0xbfb8aa3b, v81
	v_exp_f32_e32 v78, v78
	v_exp_f32_e32 v79, v79
	v_add_f32_e32 v78, 1.0, v78
	v_add_f32_e32 v79, 1.0, v79
	v_rcp_f32_e32 v78, v78
	v_rcp_f32_e32 v79, v79
	s_nop 0
	v_pk_mul_f32 v[78:79], v[80:81], v[78:79]
	s_nop 0
	v_pk_mul_f32 v[76:77], v[78:79], v[76:77]
	v_mul_f32_e32 v78, 0xbfb8aa3b, v70
	v_mul_f32_e32 v79, 0xbfb8aa3b, v71
	v_exp_f32_e32 v78, v78
	v_exp_f32_e32 v79, v79
	v_add_f32_e32 v78, 1.0, v78
	v_add_f32_e32 v79, 1.0, v79
	v_rcp_f32_e32 v78, v78
	v_rcp_f32_e32 v79, v79
	s_nop 0
	v_pk_mul_f32 v[70:71], v[70:71], v[78:79]
	s_nop 0
	v_pk_mul_f32 v[70:71], v[70:71], v[66:67]
	v_mul_f32_e32 v66, 0xbfb8aa3b, v72
	v_mul_f32_e32 v67, 0xbfb8aa3b, v73
	v_exp_f32_e32 v66, v66
	v_exp_f32_e32 v67, v67
	v_lshl_add_u64 v[78:79], v[82:83], 0, v[114:115]
	v_add_f32_e32 v66, 1.0, v66
	v_add_f32_e32 v67, 1.0, v67
	v_rcp_f32_e32 v66, v66
	v_rcp_f32_e32 v67, v67
	s_nop 0
	v_pk_mul_f32 v[66:67], v[72:73], v[66:67]
	s_nop 0
	v_pk_mul_f32 v[72:73], v[66:67], v[68:69]
	v_cvt_pk_bf16_f32 v66, v74, v75
	v_cvt_pk_bf16_f32 v67, v76, v77
	v_cvt_pk_bf16_f32 v68, v70, v71
	v_cvt_pk_bf16_f32 v69, v72, v73
	global_store_dwordx4 v[78:79], v[66:69], off sc1
	s_nop 1
	v_mul_f32_e32 v68, 0xbfb8aa3b, v62
	v_mul_f32_e32 v69, 0xbfb8aa3b, v63
	v_exp_f32_e32 v68, v68
	v_exp_f32_e32 v69, v69
	v_add_u32_e32 v66, 0x80, v146
	v_mad_i64_i32 v[66:67], s[4:5], v66, s12, v[140:141]
	v_add_f32_e32 v68, 1.0, v68
	v_add_f32_e32 v69, 1.0, v69
	v_rcp_f32_e32 v68, v68
	v_rcp_f32_e32 v69, v69
	s_nop 0
	v_pk_mul_f32 v[62:63], v[62:63], v[68:69]
	s_nop 0
	v_pk_mul_f32 v[58:59], v[62:63], v[58:59]
	v_mul_f32_e32 v62, 0xbfb8aa3b, v64
	v_mul_f32_e32 v63, 0xbfb8aa3b, v65
	v_exp_f32_e32 v62, v62
	v_exp_f32_e32 v63, v63
	v_add_f32_e32 v62, 1.0, v62
	v_add_f32_e32 v63, 1.0, v63
	v_rcp_f32_e32 v62, v62
	v_rcp_f32_e32 v63, v63
	s_nop 0
	v_pk_mul_f32 v[62:63], v[64:65], v[62:63]
	s_nop 0
	v_pk_mul_f32 v[60:61], v[62:63], v[60:61]
	v_mul_f32_e32 v62, 0xbfb8aa3b, v54
	v_mul_f32_e32 v63, 0xbfb8aa3b, v55
	v_exp_f32_e32 v62, v62
	v_exp_f32_e32 v63, v63
	v_add_f32_e32 v62, 1.0, v62
	v_add_f32_e32 v63, 1.0, v63
	v_rcp_f32_e32 v62, v62
	v_rcp_f32_e32 v63, v63
	s_nop 0
	v_pk_mul_f32 v[54:55], v[54:55], v[62:63]
	s_nop 0
	v_pk_mul_f32 v[54:55], v[54:55], v[50:51]
	v_mul_f32_e32 v50, 0xbfb8aa3b, v56
	v_mul_f32_e32 v51, 0xbfb8aa3b, v57
	v_exp_f32_e32 v50, v50
	v_exp_f32_e32 v51, v51
	v_lshl_add_u64 v[62:63], v[66:67], 0, v[114:115]
	v_add_f32_e32 v50, 1.0, v50
	v_add_f32_e32 v51, 1.0, v51
	v_rcp_f32_e32 v50, v50
	v_rcp_f32_e32 v51, v51
	s_nop 0
	v_pk_mul_f32 v[50:51], v[56:57], v[50:51]
	s_nop 0
	v_pk_mul_f32 v[56:57], v[50:51], v[52:53]
	v_cvt_pk_bf16_f32 v50, v58, v59
	v_cvt_pk_bf16_f32 v51, v60, v61
	v_cvt_pk_bf16_f32 v52, v54, v55
	v_cvt_pk_bf16_f32 v53, v56, v57
	global_store_dwordx4 v[62:63], v[50:53], off sc1
	s_nop 1
	v_mul_f32_e32 v52, 0xbfb8aa3b, v46
	v_mul_f32_e32 v53, 0xbfb8aa3b, v47
	v_exp_f32_e32 v52, v52
	v_exp_f32_e32 v53, v53
	v_add_u32_e32 v50, 0x90, v146
	v_mad_i64_i32 v[50:51], s[4:5], v50, s12, v[140:141]
	v_add_f32_e32 v52, 1.0, v52
	v_add_f32_e32 v53, 1.0, v53
	v_rcp_f32_e32 v52, v52
	v_rcp_f32_e32 v53, v53
	s_nop 0
	v_pk_mul_f32 v[46:47], v[46:47], v[52:53]
	s_nop 0
	v_pk_mul_f32 v[42:43], v[46:47], v[42:43]
	v_mul_f32_e32 v46, 0xbfb8aa3b, v48
	v_mul_f32_e32 v47, 0xbfb8aa3b, v49
	v_exp_f32_e32 v46, v46
	v_exp_f32_e32 v47, v47
	v_add_f32_e32 v46, 1.0, v46
	v_add_f32_e32 v47, 1.0, v47
	v_rcp_f32_e32 v46, v46
	v_rcp_f32_e32 v47, v47
	s_nop 0
	v_pk_mul_f32 v[46:47], v[48:49], v[46:47]
	s_nop 0
	v_pk_mul_f32 v[44:45], v[46:47], v[44:45]
	v_mul_f32_e32 v46, 0xbfb8aa3b, v38
	v_mul_f32_e32 v47, 0xbfb8aa3b, v39
	v_exp_f32_e32 v46, v46
	v_exp_f32_e32 v47, v47
	v_add_f32_e32 v46, 1.0, v46
	v_add_f32_e32 v47, 1.0, v47
	v_rcp_f32_e32 v46, v46
	v_rcp_f32_e32 v47, v47
	s_nop 0
	v_pk_mul_f32 v[38:39], v[38:39], v[46:47]
	s_nop 0
	v_pk_mul_f32 v[38:39], v[38:39], v[34:35]
	v_mul_f32_e32 v34, 0xbfb8aa3b, v40
	v_mul_f32_e32 v35, 0xbfb8aa3b, v41
	v_exp_f32_e32 v34, v34
	v_exp_f32_e32 v35, v35
	v_lshl_add_u64 v[46:47], v[50:51], 0, v[114:115]
	v_add_f32_e32 v34, 1.0, v34
	v_add_f32_e32 v35, 1.0, v35
	v_rcp_f32_e32 v34, v34
	v_rcp_f32_e32 v35, v35
	s_nop 0
	v_pk_mul_f32 v[34:35], v[40:41], v[34:35]
	s_nop 0
	v_pk_mul_f32 v[40:41], v[34:35], v[36:37]
	v_cvt_pk_bf16_f32 v34, v42, v43
	v_cvt_pk_bf16_f32 v35, v44, v45
	v_cvt_pk_bf16_f32 v36, v38, v39
	v_cvt_pk_bf16_f32 v37, v40, v41
	global_store_dwordx4 v[46:47], v[34:37], off sc1
	s_nop 1
	v_mul_f32_e32 v36, 0xbfb8aa3b, v30
	v_mul_f32_e32 v37, 0xbfb8aa3b, v31
	v_exp_f32_e32 v36, v36
	v_exp_f32_e32 v37, v37
	v_add_u32_e32 v34, 0xa0, v146
	v_mad_i64_i32 v[34:35], s[4:5], v34, s12, v[140:141]
	v_add_f32_e32 v36, 1.0, v36
	v_add_f32_e32 v37, 1.0, v37
	v_rcp_f32_e32 v36, v36
	v_rcp_f32_e32 v37, v37
	s_nop 0
	v_pk_mul_f32 v[30:31], v[30:31], v[36:37]
	s_nop 0
	v_pk_mul_f32 v[26:27], v[30:31], v[26:27]
	v_mul_f32_e32 v30, 0xbfb8aa3b, v32
	v_mul_f32_e32 v31, 0xbfb8aa3b, v33
	v_exp_f32_e32 v30, v30
	v_exp_f32_e32 v31, v31
	v_add_f32_e32 v30, 1.0, v30
	v_add_f32_e32 v31, 1.0, v31
	v_rcp_f32_e32 v30, v30
	v_rcp_f32_e32 v31, v31
	s_nop 0
	v_pk_mul_f32 v[30:31], v[32:33], v[30:31]
	s_nop 0
	v_pk_mul_f32 v[28:29], v[30:31], v[28:29]
	v_mul_f32_e32 v30, 0xbfb8aa3b, v22
	v_mul_f32_e32 v31, 0xbfb8aa3b, v23
	v_exp_f32_e32 v30, v30
	v_exp_f32_e32 v31, v31
	v_add_f32_e32 v30, 1.0, v30
	v_add_f32_e32 v31, 1.0, v31
	v_rcp_f32_e32 v30, v30
	v_rcp_f32_e32 v31, v31
	s_nop 0
	v_pk_mul_f32 v[22:23], v[22:23], v[30:31]
	s_nop 0
	v_pk_mul_f32 v[22:23], v[22:23], v[18:19]
	v_mul_f32_e32 v18, 0xbfb8aa3b, v24
	v_mul_f32_e32 v19, 0xbfb8aa3b, v25
	v_exp_f32_e32 v18, v18
	v_exp_f32_e32 v19, v19
	v_lshl_add_u64 v[30:31], v[34:35], 0, v[114:115]
	v_add_f32_e32 v18, 1.0, v18
	v_add_f32_e32 v19, 1.0, v19
	v_rcp_f32_e32 v18, v18
	v_rcp_f32_e32 v19, v19
	s_nop 0
	v_pk_mul_f32 v[18:19], v[24:25], v[18:19]
	s_nop 0
	v_pk_mul_f32 v[24:25], v[18:19], v[20:21]
	v_cvt_pk_bf16_f32 v18, v26, v27
	v_cvt_pk_bf16_f32 v19, v28, v29
	v_cvt_pk_bf16_f32 v20, v22, v23
	v_cvt_pk_bf16_f32 v21, v24, v25
	global_store_dwordx4 v[30:31], v[18:21], off sc1
	s_nop 1
	v_mul_f32_e32 v20, 0xbfb8aa3b, v14
	v_mul_f32_e32 v21, 0xbfb8aa3b, v15
	v_exp_f32_e32 v20, v20
	v_exp_f32_e32 v21, v21
	v_add_u32_e32 v18, 0xb0, v146
	v_mad_i64_i32 v[18:19], s[4:5], v18, s12, v[140:141]
	v_add_f32_e32 v20, 1.0, v20
	v_add_f32_e32 v21, 1.0, v21
	v_rcp_f32_e32 v20, v20
	v_rcp_f32_e32 v21, v21
	s_nop 0
	v_pk_mul_f32 v[14:15], v[14:15], v[20:21]
	s_nop 0
	v_pk_mul_f32 v[10:11], v[14:15], v[10:11]
	v_mul_f32_e32 v14, 0xbfb8aa3b, v16
	v_mul_f32_e32 v15, 0xbfb8aa3b, v17
	v_exp_f32_e32 v14, v14
	v_exp_f32_e32 v15, v15
	v_add_f32_e32 v14, 1.0, v14
	v_add_f32_e32 v15, 1.0, v15
	v_rcp_f32_e32 v14, v14
	v_rcp_f32_e32 v15, v15
	s_nop 0
	v_pk_mul_f32 v[14:15], v[16:17], v[14:15]
	s_nop 0
	v_pk_mul_f32 v[12:13], v[14:15], v[12:13]
	v_mul_f32_e32 v14, 0xbfb8aa3b, v6
	v_mul_f32_e32 v15, 0xbfb8aa3b, v7
	v_exp_f32_e32 v14, v14
	v_exp_f32_e32 v15, v15
	v_add_f32_e32 v14, 1.0, v14
	v_add_f32_e32 v15, 1.0, v15
	v_rcp_f32_e32 v14, v14
	v_rcp_f32_e32 v15, v15
	s_nop 0
	v_pk_mul_f32 v[6:7], v[6:7], v[14:15]
	s_nop 0
	v_pk_mul_f32 v[6:7], v[6:7], v[2:3]
	v_mul_f32_e32 v2, 0xbfb8aa3b, v8
	v_mul_f32_e32 v3, 0xbfb8aa3b, v9
	v_exp_f32_e32 v2, v2
	v_exp_f32_e32 v3, v3
	v_lshl_add_u64 v[14:15], v[18:19], 0, v[114:115]
	v_add_f32_e32 v2, 1.0, v2
	v_add_f32_e32 v3, 1.0, v3
	v_rcp_f32_e32 v2, v2
	v_rcp_f32_e32 v3, v3
	s_nop 0
	v_pk_mul_f32 v[2:3], v[8:9], v[2:3]
	s_nop 0
	v_pk_mul_f32 v[8:9], v[2:3], v[4:5]
	v_cvt_pk_bf16_f32 v2, v10, v11
	v_cvt_pk_bf16_f32 v3, v12, v13
	v_cvt_pk_bf16_f32 v4, v6, v7
	v_cvt_pk_bf16_f32 v5, v8, v9
	global_store_dwordx4 v[14:15], v[2:5], off sc1
	s_cbranch_vccz .LBB0_95
	s_waitcnt vmcnt(0)
	s_cmpk_gt_u32 s3, 0xff
	s_cbranch_scc1 .LBB0_102
	s_barrier
.LBB0_102:
	v_readlane_b32 s46, v254, 33
	s_barrier
	s_setprio 0

.LBB0_840:
	s_add_u32 s42, s76, 0x80
	s_addc_u32 s43, s77, 0
	s_add_u32 s14, s74, 0x100
	v_mov_b32_e32 v2, 0
	s_addc_u32 s15, s75, 0
	s_mov_b32 s71, 0
	v_mov_b32_e32 v3, v2
	v_mov_b32_e32 v4, v2
	v_mov_b32_e32 v5, v2
	v_mov_b32_e32 v6, v2
	v_mov_b32_e32 v7, v2
	v_mov_b32_e32 v8, v2
	v_mov_b32_e32 v9, v2
	v_mov_b32_e32 v10, v2
	v_mov_b32_e32 v11, v2
	v_mov_b32_e32 v12, v2
	v_mov_b32_e32 v13, v2
	v_mov_b32_e32 v18, v2
	v_mov_b32_e32 v19, v2
	v_mov_b32_e32 v20, v2
	v_mov_b32_e32 v21, v2
	v_mov_b32_e32 v26, v2
	v_mov_b32_e32 v27, v2
	v_mov_b32_e32 v28, v2
	v_mov_b32_e32 v29, v2
	v_mov_b32_e32 v34, v2
	v_mov_b32_e32 v35, v2
	v_mov_b32_e32 v36, v2
	v_mov_b32_e32 v37, v2
	v_mov_b32_e32 v42, v2
	v_mov_b32_e32 v43, v2
	v_mov_b32_e32 v44, v2
	v_mov_b32_e32 v45, v2
	v_mov_b32_e32 v50, v2
	v_mov_b32_e32 v51, v2
	v_mov_b32_e32 v52, v2
	v_mov_b32_e32 v53, v2
	v_mov_b32_e32 v14, v2
	v_mov_b32_e32 v15, v2
	v_mov_b32_e32 v16, v2
	v_mov_b32_e32 v17, v2
	v_mov_b32_e32 v22, v2
	v_mov_b32_e32 v23, v2
	v_mov_b32_e32 v24, v2
	v_mov_b32_e32 v25, v2
	v_mov_b32_e32 v30, v2
	v_mov_b32_e32 v31, v2
	v_mov_b32_e32 v32, v2
	v_mov_b32_e32 v33, v2
	v_mov_b32_e32 v38, v2
	v_mov_b32_e32 v39, v2
	v_mov_b32_e32 v40, v2
	v_mov_b32_e32 v41, v2
	v_mov_b32_e32 v46, v2
	v_mov_b32_e32 v47, v2
	v_mov_b32_e32 v48, v2
	v_mov_b32_e32 v49, v2
	v_mov_b32_e32 v54, v2
	v_mov_b32_e32 v55, v2
	v_mov_b32_e32 v56, v2
	v_mov_b32_e32 v57, v2
	v_mov_b32_e32 v58, v2
	v_mov_b32_e32 v59, v2
	v_mov_b32_e32 v60, v2
	v_mov_b32_e32 v61, v2
	v_mov_b32_e32 v62, v2
	v_mov_b32_e32 v63, v2
	v_mov_b32_e32 v64, v2
	v_mov_b32_e32 v65, v2
	v_mov_b32_e32 v66, v2
	v_mov_b32_e32 v67, v2
	v_mov_b32_e32 v68, v2
	v_mov_b32_e32 v69, v2
	v_mov_b32_e32 v70, v2
	v_mov_b32_e32 v71, v2
	v_mov_b32_e32 v72, v2
	v_mov_b32_e32 v73, v2
	v_mov_b32_e32 v78, v2
	v_mov_b32_e32 v79, v2
	v_mov_b32_e32 v80, v2
	v_mov_b32_e32 v81, v2
	v_mov_b32_e32 v86, v2
	v_mov_b32_e32 v87, v2
	v_mov_b32_e32 v88, v2
	v_mov_b32_e32 v89, v2
	v_mov_b32_e32 v94, v2
	v_mov_b32_e32 v95, v2
	v_mov_b32_e32 v96, v2
	v_mov_b32_e32 v97, v2
	v_mov_b32_e32 v102, v2
	v_mov_b32_e32 v103, v2
	v_mov_b32_e32 v104, v2
	v_mov_b32_e32 v105, v2
	v_mov_b32_e32 v110, v2
	v_mov_b32_e32 v111, v2
	v_mov_b32_e32 v112, v2
	v_mov_b32_e32 v113, v2
	v_mov_b32_e32 v118, v2
	v_mov_b32_e32 v119, v2
	v_mov_b32_e32 v120, v2
	v_mov_b32_e32 v121, v2
	v_mov_b32_e32 v74, v2
	v_mov_b32_e32 v75, v2
	v_mov_b32_e32 v76, v2
	v_mov_b32_e32 v77, v2
	v_mov_b32_e32 v82, v2
	v_mov_b32_e32 v83, v2
	v_mov_b32_e32 v84, v2
	v_mov_b32_e32 v85, v2
	v_mov_b32_e32 v90, v2
	v_mov_b32_e32 v91, v2
	v_mov_b32_e32 v92, v2
	v_mov_b32_e32 v93, v2
	v_mov_b32_e32 v98, v2
	v_mov_b32_e32 v99, v2
	v_mov_b32_e32 v100, v2
	v_mov_b32_e32 v101, v2
	v_mov_b32_e32 v106, v2
	v_mov_b32_e32 v107, v2
	v_mov_b32_e32 v108, v2
	v_mov_b32_e32 v109, v2
	v_mov_b32_e32 v114, v2
	v_mov_b32_e32 v115, v2
	v_mov_b32_e32 v116, v2
	v_mov_b32_e32 v117, v2
	v_mov_b32_e32 v122, v2
	v_mov_b32_e32 v123, v2
	v_mov_b32_e32 v124, v2
	v_mov_b32_e32 v125, v2
	v_mov_b32_e32 v126, v2
	v_mov_b32_e32 v127, v2
	v_mov_b32_e32 v128, v2
	v_mov_b32_e32 v129, v2
	v_readfirstlane_b32 s98, v202
	s_nop 3
	s_bfe_u32 s98, s98, 0x40006
	s_cmp_ge_u32 s98, 4
	s_cbranch_scc1 .Lgp_gs
	s_setprio 1
.Lgp_gs:
.LBB0_841:
	s_add_i32 vcc_lo, s71, 2
	s_add_u32 s16, s42, 0x80
	s_addc_u32 s17, s43, 0
	s_add_i32 s84, 0, 0x10000
	v_add_u32_e32 v156, s84, v145
	ds_read_b128 v[140:143], v156
	ds_read_b128 v[148:151], v156 offset:1024
	ds_read_b128 v[152:155], v156 offset:2048
	ds_read_b128 v[156:159], v156 offset:3072
	s_cmp_eq_u32 s12, s71
	s_cselect_b32 s75, s73, s17
	s_cselect_b32 s74, s72, s16
	s_cselect_b32 s77, s45, s15
	s_cselect_b32 s76, s44, s14
	v_lshl_add_u64 v[168:169], s[42:43], 0, v[136:137]
	s_add_i32 m0, s91, 0xc000
	ds_read_b128 v[160:163], v147
	ds_read_b128 v[164:167], v147 offset:1024
	ds_read_b128 v[176:179], v147 offset:2048
	ds_read_b128 v[180:183], v147 offset:3072
	ds_read_b128 v[184:187], v147 offset:4096
	ds_read_b128 v[188:191], v147 offset:5120
	ds_read_b128 v[192:195], v147 offset:6144
	ds_read_b128 v[196:199], v147 offset:7168
	global_load_lds_dwordx4 v[168:169], off
	v_lshl_add_u64 v[168:169], s[42:43], 0, v[138:139]
	s_add_i32 m0, s91, 0xe000
	s_nop 0
	global_load_lds_dwordx4 v[168:169], off
	s_waitcnt lgkmcnt(8)
	s_barrier
	s_waitcnt lgkmcnt(0)
	s_waitcnt lgkmcnt(0)
	v_mfma_f32_16x16x32_bf16 v[126:129], v[140:143], v[160:163], v[126:129]
	v_mfma_f32_16x16x32_bf16 v[122:125], v[152:155], v[160:163], v[122:125]
	v_mfma_f32_16x16x32_bf16 v[114:117], v[140:143], v[176:179], v[114:117]
	v_mfma_f32_16x16x32_bf16 v[106:109], v[152:155], v[176:179], v[106:109]
	v_mfma_f32_16x16x32_bf16 v[98:101], v[140:143], v[184:187], v[98:101]
	v_mfma_f32_16x16x32_bf16 v[90:93], v[152:155], v[184:187], v[90:93]
	v_mfma_f32_16x16x32_bf16 v[82:85], v[140:143], v[192:195], v[82:85]
	v_mfma_f32_16x16x32_bf16 v[74:77], v[152:155], v[192:195], v[74:77]
	v_mfma_f32_16x16x32_bf16 v[126:129], v[148:151], v[164:167], v[126:129]
	v_mfma_f32_16x16x32_bf16 v[122:125], v[156:159], v[164:167], v[122:125]
	v_mfma_f32_16x16x32_bf16 v[114:117], v[148:151], v[180:183], v[114:117]
	v_mfma_f32_16x16x32_bf16 v[106:109], v[156:159], v[180:183], v[106:109]
	v_mfma_f32_16x16x32_bf16 v[98:101], v[148:151], v[188:191], v[98:101]
	v_mfma_f32_16x16x32_bf16 v[90:93], v[156:159], v[188:191], v[90:93]
	v_mfma_f32_16x16x32_bf16 v[82:85], v[148:151], v[196:199], v[82:85]
	v_mfma_f32_16x16x32_bf16 v[74:77], v[156:159], v[196:199], v[74:77]
	s_barrier
	s_add_i32 s16, 0, 0x14000
	v_add_u32_e32 v168, s16, v145
	s_add_i32 s17, s84, s87
	ds_read_b128 v[228:231], v168
	ds_read_b128 v[232:235], v168 offset:1024
	ds_read_b128 v[236:239], v168 offset:2048
	ds_read_b128 v[240:243], v168 offset:3072
	v_lshl_add_u64 v[168:169], s[76:77], 0, v[0:1]
	s_mov_b32 m0, s17
	v_lshl_add_u64 v[200:201], s[76:77], 0, v[134:135]
	global_load_lds_dwordx4 v[168:169], off
	s_add_i32 m0, s17, 0x2000
	s_nop 0
	global_load_lds_dwordx4 v[200:201], off
	s_barrier
	s_waitcnt lgkmcnt(0)
	s_waitcnt lgkmcnt(0)
	v_mfma_f32_16x16x32_bf16 v[118:121], v[228:231], v[160:163], v[118:121]
	v_mfma_f32_16x16x32_bf16 v[110:113], v[236:239], v[160:163], v[110:113]
	v_mfma_f32_16x16x32_bf16 v[102:105], v[228:231], v[176:179], v[102:105]
	v_mfma_f32_16x16x32_bf16 v[94:97], v[236:239], v[176:179], v[94:97]
	v_mfma_f32_16x16x32_bf16 v[86:89], v[228:231], v[184:187], v[86:89]
	v_mfma_f32_16x16x32_bf16 v[78:81], v[236:239], v[184:187], v[78:81]
	v_mfma_f32_16x16x32_bf16 v[70:73], v[228:231], v[192:195], v[70:73]
	v_mfma_f32_16x16x32_bf16 v[66:69], v[236:239], v[192:195], v[66:69]
	v_mfma_f32_16x16x32_bf16 v[118:121], v[232:235], v[164:167], v[118:121]
	v_mfma_f32_16x16x32_bf16 v[110:113], v[240:243], v[164:167], v[110:113]
	v_mfma_f32_16x16x32_bf16 v[102:105], v[232:235], v[180:183], v[102:105]
	v_mfma_f32_16x16x32_bf16 v[94:97], v[240:243], v[180:183], v[94:97]
	v_mfma_f32_16x16x32_bf16 v[86:89], v[232:235], v[188:191], v[86:89]
	v_mfma_f32_16x16x32_bf16 v[78:81], v[240:243], v[188:191], v[78:81]
	v_mfma_f32_16x16x32_bf16 v[70:73], v[232:235], v[196:199], v[70:73]
	v_mfma_f32_16x16x32_bf16 v[66:69], v[240:243], v[196:199], v[66:69]
	s_mov_b32 m0, s91
	v_lshl_add_u64 v[244:245], s[74:75], 0, v[130:131]
	s_barrier
	ds_read_b128 v[160:163], v147 offset:16384
	ds_read_b128 v[164:167], v147 offset:17408
	ds_read_b128 v[176:179], v147 offset:18432
	ds_read_b128 v[180:183], v147 offset:19456
	ds_read_b128 v[184:187], v147 offset:20480
	ds_read_b128 v[188:191], v147 offset:21504
	ds_read_b128 v[192:195], v147 offset:22528
	ds_read_b128 v[196:199], v147 offset:23552
	global_load_lds_dwordx4 v[244:245], off
	v_lshl_add_u64 v[246:247], s[74:75], 0, v[132:133]
	s_mov_b32 m0, s92
	s_nop 0
	global_load_lds_dwordx4 v[246:247], off
	s_barrier
	s_waitcnt lgkmcnt(0)
	s_waitcnt lgkmcnt(0)
	v_mfma_f32_16x16x32_bf16 v[62:65], v[140:143], v[160:163], v[62:65]
	v_mfma_f32_16x16x32_bf16 v[58:61], v[152:155], v[160:163], v[58:61]
	v_mfma_f32_16x16x32_bf16 v[54:57], v[140:143], v[176:179], v[54:57]
	v_mfma_f32_16x16x32_bf16 v[46:49], v[152:155], v[176:179], v[46:49]
	v_mfma_f32_16x16x32_bf16 v[38:41], v[140:143], v[184:187], v[38:41]
	v_mfma_f32_16x16x32_bf16 v[30:33], v[152:155], v[184:187], v[30:33]
	v_mfma_f32_16x16x32_bf16 v[22:25], v[140:143], v[192:195], v[22:25]
	v_mfma_f32_16x16x32_bf16 v[14:17], v[152:155], v[192:195], v[14:17]
	v_mfma_f32_16x16x32_bf16 v[62:65], v[148:151], v[164:167], v[62:65]
	v_mfma_f32_16x16x32_bf16 v[58:61], v[156:159], v[164:167], v[58:61]
	v_mfma_f32_16x16x32_bf16 v[54:57], v[148:151], v[180:183], v[54:57]
	v_mfma_f32_16x16x32_bf16 v[46:49], v[156:159], v[180:183], v[46:49]
	v_mfma_f32_16x16x32_bf16 v[38:41], v[148:151], v[188:191], v[38:41]
	v_mfma_f32_16x16x32_bf16 v[30:33], v[156:159], v[188:191], v[30:33]
	v_mfma_f32_16x16x32_bf16 v[22:25], v[148:151], v[196:199], v[22:25]
	v_mfma_f32_16x16x32_bf16 v[14:17], v[156:159], v[196:199], v[14:17]
	s_barrier
	s_add_u32 s76, s76, s64
	s_addc_u32 s77, s77, 0
	s_add_i32 s16, s16, s87
	v_lshl_add_u64 v[248:249], s[76:77], 0, v[0:1]
	s_mov_b32 m0, s16
	v_lshl_add_u64 v[250:251], s[76:77], 0, v[134:135]
	global_load_lds_dwordx4 v[248:249], off
	s_add_i32 m0, s16, 0x2000
	s_nop 0
	global_load_lds_dwordx4 v[250:251], off
	s_waitcnt vmcnt(6)
	s_barrier
	v_mfma_f32_16x16x32_bf16 v[50:53], v[228:231], v[160:163], v[50:53]
	v_mfma_f32_16x16x32_bf16 v[42:45], v[236:239], v[160:163], v[42:45]
	v_mfma_f32_16x16x32_bf16 v[34:37], v[228:231], v[176:179], v[34:37]
	v_mfma_f32_16x16x32_bf16 v[26:29], v[236:239], v[176:179], v[26:29]
	v_mfma_f32_16x16x32_bf16 v[18:21], v[228:231], v[184:187], v[18:21]
	v_mfma_f32_16x16x32_bf16 v[10:13], v[236:239], v[184:187], v[10:13]
	v_mfma_f32_16x16x32_bf16 v[6:9], v[228:231], v[192:195], v[6:9]
	v_mfma_f32_16x16x32_bf16 v[2:5], v[236:239], v[192:195], v[2:5]
	v_mfma_f32_16x16x32_bf16 v[50:53], v[232:235], v[164:167], v[50:53]
	v_mfma_f32_16x16x32_bf16 v[42:45], v[240:243], v[164:167], v[42:45]
	v_mfma_f32_16x16x32_bf16 v[34:37], v[232:235], v[180:183], v[34:37]
	v_mfma_f32_16x16x32_bf16 v[26:29], v[240:243], v[180:183], v[26:29]
	v_mfma_f32_16x16x32_bf16 v[18:21], v[232:235], v[188:191], v[18:21]
	v_mfma_f32_16x16x32_bf16 v[10:13], v[240:243], v[188:191], v[10:13]
	v_mfma_f32_16x16x32_bf16 v[6:9], v[232:235], v[196:199], v[6:9]
	v_mfma_f32_16x16x32_bf16 v[2:5], v[240:243], v[196:199], v[2:5]
	s_add_i32 s16, 0, 0x18000
	v_add_u32_e32 v156, s16, v145
	s_barrier
	ds_read_b128 v[140:143], v156
	ds_read_b128 v[148:151], v156 offset:1024
	ds_read_b128 v[152:155], v156 offset:2048
	ds_read_b128 v[156:159], v156 offset:3072
	s_add_u32 s74, s74, s64
	s_addc_u32 s75, s75, 0
	s_mov_b32 m0, s93
	v_lshl_add_u64 v[228:229], s[74:75], 0, v[130:131]
	ds_read_b128 v[160:163], v147 offset:32768
	ds_read_b128 v[164:167], v147 offset:33792
	ds_read_b128 v[176:179], v147 offset:34816
	ds_read_b128 v[180:183], v147 offset:35840
	ds_read_b128 v[184:187], v147 offset:36864
	ds_read_b128 v[188:191], v147 offset:37888
	ds_read_b128 v[192:195], v147 offset:38912
	ds_read_b128 v[196:199], v147 offset:39936
	global_load_lds_dwordx4 v[228:229], off
	v_lshl_add_u64 v[228:229], s[74:75], 0, v[132:133]
	s_mov_b32 m0, s94
	s_nop 0
	global_load_lds_dwordx4 v[228:229], off
	s_waitcnt lgkmcnt(8)
	s_barrier
	s_waitcnt lgkmcnt(0)
	s_waitcnt lgkmcnt(0)
	v_mfma_f32_16x16x32_bf16 v[126:129], v[140:143], v[160:163], v[126:129]
	v_mfma_f32_16x16x32_bf16 v[122:125], v[152:155], v[160:163], v[122:125]
	v_mfma_f32_16x16x32_bf16 v[114:117], v[140:143], v[176:179], v[114:117]
	v_mfma_f32_16x16x32_bf16 v[106:109], v[152:155], v[176:179], v[106:109]
	v_mfma_f32_16x16x32_bf16 v[98:101], v[140:143], v[184:187], v[98:101]
	v_mfma_f32_16x16x32_bf16 v[90:93], v[152:155], v[184:187], v[90:93]
	v_mfma_f32_16x16x32_bf16 v[82:85], v[140:143], v[192:195], v[82:85]
	v_mfma_f32_16x16x32_bf16 v[74:77], v[152:155], v[192:195], v[74:77]
	v_mfma_f32_16x16x32_bf16 v[126:129], v[148:151], v[164:167], v[126:129]
	v_mfma_f32_16x16x32_bf16 v[122:125], v[156:159], v[164:167], v[122:125]
	v_mfma_f32_16x16x32_bf16 v[114:117], v[148:151], v[180:183], v[114:117]
	v_mfma_f32_16x16x32_bf16 v[106:109], v[156:159], v[180:183], v[106:109]
	v_mfma_f32_16x16x32_bf16 v[98:101], v[148:151], v[188:191], v[98:101]
	v_mfma_f32_16x16x32_bf16 v[90:93], v[156:159], v[188:191], v[90:93]
	v_mfma_f32_16x16x32_bf16 v[82:85], v[148:151], v[196:199], v[82:85]
	v_mfma_f32_16x16x32_bf16 v[74:77], v[156:159], v[196:199], v[74:77]
	s_barrier
	s_add_i32 s17, 0, 0x1c000
	s_add_i32 s16, s16, s87
	v_add_u32_e32 v175, s17, v145
	v_lshl_add_u64 v[168:169], v[168:169], 0, s[34:35]
	s_mov_b32 m0, s16
	ds_read_b128 v[228:231], v175
	ds_read_b128 v[232:235], v175 offset:1024
	ds_read_b128 v[236:239], v175 offset:2048
	ds_read_b128 v[240:243], v175 offset:3072
	global_load_lds_dwordx4 v[168:169], off
	v_lshl_add_u64 v[168:169], v[200:201], 0, s[34:35]
	s_add_i32 m0, s16, 0x2000
	s_nop 0
	global_load_lds_dwordx4 v[168:169], off
	s_barrier
	s_waitcnt lgkmcnt(0)
	s_waitcnt lgkmcnt(0)
	v_mfma_f32_16x16x32_bf16 v[118:121], v[228:231], v[160:163], v[118:121]
	v_mfma_f32_16x16x32_bf16 v[110:113], v[236:239], v[160:163], v[110:113]
	v_mfma_f32_16x16x32_bf16 v[102:105], v[228:231], v[176:179], v[102:105]
	v_mfma_f32_16x16x32_bf16 v[94:97], v[236:239], v[176:179], v[94:97]
	v_mfma_f32_16x16x32_bf16 v[86:89], v[228:231], v[184:187], v[86:89]
	v_mfma_f32_16x16x32_bf16 v[78:81], v[236:239], v[184:187], v[78:81]
	v_mfma_f32_16x16x32_bf16 v[70:73], v[228:231], v[192:195], v[70:73]
	v_mfma_f32_16x16x32_bf16 v[66:69], v[236:239], v[192:195], v[66:69]
	v_mfma_f32_16x16x32_bf16 v[118:121], v[232:235], v[164:167], v[118:121]
	v_mfma_f32_16x16x32_bf16 v[110:113], v[240:243], v[164:167], v[110:113]
	v_mfma_f32_16x16x32_bf16 v[102:105], v[232:235], v[180:183], v[102:105]
	v_mfma_f32_16x16x32_bf16 v[94:97], v[240:243], v[180:183], v[94:97]
	v_mfma_f32_16x16x32_bf16 v[86:89], v[232:235], v[188:191], v[86:89]
	v_mfma_f32_16x16x32_bf16 v[78:81], v[240:243], v[188:191], v[78:81]
	v_mfma_f32_16x16x32_bf16 v[70:73], v[232:235], v[196:199], v[70:73]
	v_mfma_f32_16x16x32_bf16 v[66:69], v[240:243], v[196:199], v[66:69]
	s_mov_b32 m0, s96
	v_lshl_add_u64 v[168:169], v[244:245], 0, s[34:35]
	s_barrier
	ds_read_b128 v[160:163], v147 offset:49152
	ds_read_b128 v[164:167], v147 offset:50176
	ds_read_b128 v[176:179], v147 offset:51200
	ds_read_b128 v[180:183], v147 offset:52224
	ds_read_b128 v[184:187], v147 offset:53248
	ds_read_b128 v[188:191], v147 offset:54272
	ds_read_b128 v[192:195], v147 offset:55296
	ds_read_b128 v[196:199], v147 offset:56320
	global_load_lds_dwordx4 v[168:169], off
	v_lshl_add_u64 v[168:169], v[246:247], 0, s[34:35]
	s_mov_b32 m0, s97
	s_nop 0
	global_load_lds_dwordx4 v[168:169], off
	s_barrier
	s_waitcnt lgkmcnt(0)
	s_waitcnt lgkmcnt(0)
	v_mfma_f32_16x16x32_bf16 v[62:65], v[140:143], v[160:163], v[62:65]
	v_mfma_f32_16x16x32_bf16 v[58:61], v[152:155], v[160:163], v[58:61]
	v_mfma_f32_16x16x32_bf16 v[54:57], v[140:143], v[176:179], v[54:57]
	v_mfma_f32_16x16x32_bf16 v[46:49], v[152:155], v[176:179], v[46:49]
	v_mfma_f32_16x16x32_bf16 v[38:41], v[140:143], v[184:187], v[38:41]
	v_mfma_f32_16x16x32_bf16 v[30:33], v[152:155], v[184:187], v[30:33]
	v_mfma_f32_16x16x32_bf16 v[22:25], v[140:143], v[192:195], v[22:25]
	v_mfma_f32_16x16x32_bf16 v[14:17], v[152:155], v[192:195], v[14:17]
	v_mfma_f32_16x16x32_bf16 v[62:65], v[148:151], v[164:167], v[62:65]
	v_mfma_f32_16x16x32_bf16 v[58:61], v[156:159], v[164:167], v[58:61]
	v_mfma_f32_16x16x32_bf16 v[54:57], v[148:151], v[180:183], v[54:57]
	v_mfma_f32_16x16x32_bf16 v[46:49], v[156:159], v[180:183], v[46:49]
	v_mfma_f32_16x16x32_bf16 v[38:41], v[148:151], v[188:191], v[38:41]
	v_mfma_f32_16x16x32_bf16 v[30:33], v[156:159], v[188:191], v[30:33]
	v_mfma_f32_16x16x32_bf16 v[22:25], v[148:151], v[196:199], v[22:25]
	v_mfma_f32_16x16x32_bf16 v[14:17], v[156:159], v[196:199], v[14:17]
	s_barrier
	s_add_i32 s16, s17, s87
	v_lshl_add_u64 v[140:141], v[248:249], 0, s[34:35]
	s_mov_b32 m0, s16
	s_nop 0
	global_load_lds_dwordx4 v[140:141], off
	v_lshl_add_u64 v[140:141], v[250:251], 0, s[34:35]
	s_add_i32 m0, s16, 0x2000
	s_nop 0
	global_load_lds_dwordx4 v[140:141], off
	s_waitcnt vmcnt(6)
	s_barrier
	v_mfma_f32_16x16x32_bf16 v[50:53], v[228:231], v[160:163], v[50:53]
	v_mfma_f32_16x16x32_bf16 v[42:45], v[236:239], v[160:163], v[42:45]
	v_mfma_f32_16x16x32_bf16 v[34:37], v[228:231], v[176:179], v[34:37]
	v_mfma_f32_16x16x32_bf16 v[26:29], v[236:239], v[176:179], v[26:29]
	v_mfma_f32_16x16x32_bf16 v[18:21], v[228:231], v[184:187], v[18:21]
	v_mfma_f32_16x16x32_bf16 v[10:13], v[236:239], v[184:187], v[10:13]
	v_mfma_f32_16x16x32_bf16 v[6:9], v[228:231], v[192:195], v[6:9]
	v_mfma_f32_16x16x32_bf16 v[2:5], v[236:239], v[192:195], v[2:5]
	v_mfma_f32_16x16x32_bf16 v[50:53], v[232:235], v[164:167], v[50:53]
	v_mfma_f32_16x16x32_bf16 v[42:45], v[240:243], v[164:167], v[42:45]
	v_mfma_f32_16x16x32_bf16 v[34:37], v[232:235], v[180:183], v[34:37]
	v_mfma_f32_16x16x32_bf16 v[26:29], v[240:243], v[180:183], v[26:29]
	v_mfma_f32_16x16x32_bf16 v[18:21], v[232:235], v[188:191], v[18:21]
	v_mfma_f32_16x16x32_bf16 v[10:13], v[240:243], v[188:191], v[10:13]
	v_mfma_f32_16x16x32_bf16 v[6:9], v[232:235], v[196:199], v[6:9]
	v_mfma_f32_16x16x32_bf16 v[2:5], v[240:243], v[196:199], v[2:5]
	s_add_u32 s42, s42, 0x100
	s_addc_u32 s43, s43, 0
	s_add_u32 s14, s14, 0x100
	s_addc_u32 s15, s15, 0
	s_cmp_ge_u32 vcc_lo, s18
	s_mov_b32 s71, vcc_lo
	s_barrier
	s_cbranch_scc0 .LBB0_841
	s_mul_hi_i32 s15, s60, s95
	s_mul_i32 s14, s60, s95
	s_lshl_b64 s[14:15], s[14:15], 1
	v_lshl_add_u32 v148, s83, 8, v144
	s_add_u32 s74, s58, s14
	v_lshl_or_b32 v140, s82, 8, v146
	s_addc_u32 s75, s59, s15
	v_mad_i64_i32 v[142:143], s[14:15], v148, s21, 0
	v_lshl_add_u64 v[142:143], v[142:143], 1, s[74:75]
	v_cmp_gt_i32_e32 vcc, s19, v140
	v_ashrrev_i32_e32 v141, 31, v140
	s_and_saveexec_b64 s[14:15], vcc
	s_cbranch_execz .LBB0_844
	v_cvt_pk_bf16_f32 v126, v126, v127
	v_cvt_pk_bf16_f32 v127, v128, v129
	v_cvt_pk_bf16_f32 v128, v122, v123
	v_cvt_pk_bf16_f32 v129, v124, v125
	v_lshl_add_u64 v[122:123], v[140:141], 1, v[142:143]
	global_store_dwordx4 v[122:123], v[126:129], off sc1
	s_setprio 0
